# sel pair-visit bodies: bit-exact instruction trimming (0.125 score scale folded into exp-argument fma, dead zero-inits of fp8 pack regs, x+0 copies removed)
# speedup vs baseline: 1.0547x; 1.0039x over previous
.Lsel_done_1:
	v_mov_b32_e32 v240, s100
	s_nop 1
	v_mov_b32_e32 v1, s94
	v_mov_b32_e32 v239, s98
	v_lshlrev_b32_e32 v2, 12, v1
	s_waitcnt vmcnt(16)
	v_lshlrev_b32_e32 v100, 12, v239
	v_ashrrev_i32_e32 v3, 31, v2
	v_ashrrev_i32_e32 v101, 31, v100
	v_lshl_add_u64 v[4:5], v[200:201], 0, v[2:3]
	v_lshl_add_u64 v[2:3], v[198:199], 0, v[2:3]
	v_lshl_add_u64 v[102:103], v[200:201], 0, v[100:101]
	v_lshl_add_u64 v[100:101], v[198:199], 0, v[100:101]
	global_load_dwordx4 v[128:131], v[4:5], off
	global_load_dwordx4 v[124:127], v[4:5], off offset:1024
	global_load_dwordx4 v[120:123], v[4:5], off offset:2048
	global_load_dwordx4 v[116:119], v[4:5], off offset:3072
	global_load_dwordx4 v[48:51], v[2:3], off
	global_load_dwordx4 v[44:47], v[2:3], off offset:1024
	global_load_dwordx4 v[6:9], v[2:3], off offset:2048
	s_nop 0
	global_load_dwordx4 v[2:5], v[2:3], off offset:3072
	s_nop 0
	global_load_dwordx4 v[144:147], v[102:103], off
	global_load_dwordx4 v[140:143], v[102:103], off offset:1024
	global_load_dwordx4 v[136:139], v[102:103], off offset:2048
	global_load_dwordx4 v[132:135], v[102:103], off offset:3072
	global_load_dwordx4 v[112:115], v[100:101], off
	global_load_dwordx4 v[108:111], v[100:101], off offset:1024
	global_load_dwordx4 v[104:107], v[100:101], off offset:2048
	s_nop 0
	global_load_dwordx4 v[100:103], v[100:101], off offset:3072
	v_cmp_lt_i32_e64 s[0:1], -1, v236
	s_and_saveexec_b64 s[12:13], s[0:1]
	s_xor_b64 s[20:21], exec, s[12:13]
	s_cbranch_execz .LBB0_586
	v_lshlrev_b32_e32 v236, 1, v236
	v_cmp_ne_u32_e64 s[12:13], v208, v236
	v_cmp_ge_i32_e64 s[14:15], v234, v229
	v_cmp_eq_u32_e64 s[0:1], v208, v236
	s_or_b64 s[12:13], s[12:13], s[14:15]
	s_mov_b64 s[14:15], -1
	s_and_saveexec_b64 s[22:23], s[12:13]
	v_or_b32_e32 v234, 1, v236
	v_cmp_eq_u32_e64 s[12:13], v208, v234
	v_cmp_lt_i32_e64 s[14:15], v235, v229
	s_and_b64 s[12:13], s[12:13], s[14:15]
	s_orn2_b64 s[14:15], s[12:13], exec
	s_or_b64 exec, exec, s[22:23]
	v_cndmask_b32_e64 v243, 0, v151, s[0:1]
	v_cndmask_b32_e64 v242, 0, v150, s[0:1]
	v_cndmask_b32_e64 v245, 0, v11, s[0:1]
	v_cndmask_b32_e64 v244, 0, v10, s[0:1]
	s_waitcnt vmcnt(16)
	v_mfma_f32_16x16x32_fp8_fp8 v[234:237], v[80:81], v[242:243], 0
	s_and_b64 s[12:13], s[0:1], s[14:15]
	v_mfma_f32_16x16x32_fp8_fp8 v[80:83], v[82:83], v[244:245], v[234:237]
	s_nop 5
	v_cndmask_b32_e64 v235, v151, 0, s[0:1]
	v_cndmask_b32_e64 v234, v150, 0, s[0:1]
	v_cndmask_b32_e64 v237, v11, 0, s[0:1]
	v_cndmask_b32_e64 v236, v10, 0, s[0:1]
	v_mfma_f32_16x16x32_fp8_fp8 v[80:83], v[96:97], v[234:235], v[80:83]
	s_xor_b64 s[0:1], s[0:1], -1
	s_and_b64 s[0:1], s[14:15], s[0:1]
	v_mfma_f32_16x16x32_fp8_fp8 v[80:83], v[98:99], v[236:237], v[80:83]
	v_mfma_f32_16x16x32_fp8_fp8 v[96:99], v[76:77], v[242:243], 0
	v_mfma_f32_16x16x32_fp8_fp8 v[76:79], v[78:79], v[244:245], v[96:99]
	s_nop 5
	v_mfma_f32_16x16x32_fp8_fp8 v[76:79], v[92:93], v[234:235], v[76:79]
	v_mfma_f32_16x16x32_fp8_fp8 v[76:79], v[94:95], v[236:237], v[76:79]
	v_mfma_f32_16x16x32_fp8_fp8 v[92:95], v[72:73], v[242:243], 0
	v_mfma_f32_16x16x32_fp8_fp8 v[72:75], v[74:75], v[244:245], v[92:95]
	s_nop 5
	v_mfma_f32_16x16x32_fp8_fp8 v[72:75], v[88:89], v[234:235], v[72:75]
	v_mfma_f32_16x16x32_fp8_fp8 v[72:75], v[90:91], v[236:237], v[72:75]
	v_mfma_f32_16x16x32_fp8_fp8 v[88:91], v[68:69], v[242:243], 0
	v_mfma_f32_16x16x32_fp8_fp8 v[68:71], v[70:71], v[244:245], v[88:91]
	s_nop 5
	v_mfma_f32_16x16x32_fp8_fp8 v[68:71], v[84:85], v[234:235], v[68:71]
	v_max_f32_e32 v84, v80, v81
	v_max_f32_e32 v85, v82, v83
	v_mfma_f32_16x16x32_fp8_fp8 v[68:71], v[86:87], v[236:237], v[68:71]
	v_max_f32_e32 v86, v78, v79
	v_max3_f32 v86, v76, v77, v86
	v_max3_f32 v84, v84, v85, v86
	v_max_f32_e32 v85, v74, v75
	v_max3_f32 v85, v72, v73, v85
	s_nop 2
	v_max_f32_e32 v86, v70, v71
	v_max3_f32 v86, v68, v69, v86
	v_max3_f32 v84, v84, v85, v86
	ds_bpermute_b32 v85, v223, v84
	s_waitcnt lgkmcnt(0)
	v_max_f32_e32 v85, v85, v85
	v_max_f32_e32 v84, v84, v85
	ds_bpermute_b32 v85, v224, v84
	s_waitcnt lgkmcnt(0)
	v_max_f32_e32 v84, v84, v85
	v_mul_f32_e64 v84, v84, s76
	v_max_f32_e32 v84, v238, v84
	v_cndmask_b32_e64 v85, v238, v84, s[14:15]
	v_sub_f32_e32 v88, 0x41000000, v85
	v_fma_f32 v80, v80, s76, v88
	v_fma_f32 v81, v81, s76, v88
	v_fma_f32 v76, v76, s76, v88
	v_fma_f32 v77, v77, s76, v88
	v_exp_f32_e32 v80, v80
	v_exp_f32_e32 v81, v81
	v_exp_f32_e32 v76, v76
	v_exp_f32_e32 v77, v77
	v_fma_f32 v82, v82, s76, v88
	v_fma_f32 v83, v83, s76, v88
	v_fma_f32 v78, v78, s76, v88
	v_fma_f32 v79, v79, s76, v88
	v_exp_f32_e32 v82, v82
	v_exp_f32_e32 v83, v83
	v_exp_f32_e32 v78, v78
	v_exp_f32_e32 v79, v79
	v_cvt_pk_fp8_f32 v90, v76, v77
	v_cvt_pk_fp8_f32 v89, v80, v81
	v_sub_f32_e32 v84, v238, v85
	v_exp_f32_e32 v84, v84
	v_cvt_pk_fp8_f32 v90, v78, v79 op_sel:[0,0,1]
	v_cvt_pk_fp8_f32 v89, v82, v83 op_sel:[0,0,1]
	v_fma_f32 v72, v72, s76, v88
	v_pk_mul_f32 v[42:43], v[42:43], v[84:85] op_sel_hi:[1,0]
	v_pk_mul_f32 v[40:41], v[40:41], v[84:85] op_sel_hi:[1,0]
	v_cndmask_b32_e64 v87, 0, v90, s[12:13]
	v_cndmask_b32_e64 v86, 0, v89, s[12:13]
	v_pk_mul_f32 v[38:39], v[38:39], v[84:85] op_sel_hi:[1,0]
	v_pk_mul_f32 v[36:37], v[36:37], v[84:85] op_sel_hi:[1,0]
	v_pk_mul_f32 v[34:35], v[34:35], v[84:85] op_sel_hi:[1,0]
	v_pk_mul_f32 v[32:33], v[32:33], v[84:85] op_sel_hi:[1,0]
	v_fma_f32 v73, v73, s76, v88
	v_mfma_f32_16x16x32_fp8_fp8 v[40:43], v[24:25], v[86:87], v[40:43]
	v_fma_f32 v24, v68, s76, v88
	v_exp_f32_e32 v72, v72
	v_exp_f32_e32 v73, v73
	v_mfma_f32_16x16x32_fp8_fp8 v[36:39], v[20:21], v[86:87], v[36:39]
	v_exp_f32_e32 v68, v24
	v_pk_mul_f32 v[30:31], v[30:31], v[84:85] op_sel_hi:[1,0]
	v_pk_mul_f32 v[28:29], v[28:29], v[84:85] op_sel_hi:[1,0]
	v_mfma_f32_16x16x32_fp8_fp8 v[32:35], v[16:17], v[86:87], v[32:35]
	v_fma_f32 v16, v69, s76, v88
	v_exp_f32_e32 v69, v16
	v_fma_f32 v16, v70, s76, v88
	v_mfma_f32_16x16x32_fp8_fp8 v[28:31], v[12:13], v[86:87], v[28:31]
	v_cndmask_b32_e64 v13, 0, v90, s[0:1]
	v_cndmask_b32_e64 v12, 0, v89, s[0:1]
	v_fma_f32 v74, v74, s76, v88
	v_fma_f32 v75, v75, s76, v88
	v_mfma_f32_16x16x32_fp8_fp8 v[36:39], v[60:61], v[12:13], v[36:39]
	v_exp_f32_e32 v60, v16
	v_fma_f32 v16, v71, s76, v88
	v_exp_f32_e32 v74, v74
	v_mfma_f32_16x16x32_fp8_fp8 v[32:35], v[56:57], v[12:13], v[32:35]
	v_exp_f32_e32 v75, v75
	v_exp_f32_e32 v61, v16
	v_cvt_pk_fp8_f32 v57, v68, v69
	v_cvt_pk_fp8_f32 v56, v72, v73
	v_mfma_f32_16x16x32_fp8_fp8 v[40:43], v[64:65], v[12:13], v[40:43]
	v_mov_b32_e32 v238, v85
	v_cvt_pk_fp8_f32 v57, v60, v61 op_sel:[0,0,1]
	v_cvt_pk_fp8_f32 v56, v74, v75 op_sel:[0,0,1]
	v_mfma_f32_16x16x32_fp8_fp8 v[28:31], v[52:53], v[12:13], v[28:31]
	v_cndmask_b32_e64 v13, 0, v57, s[12:13]
	v_cndmask_b32_e64 v12, 0, v56, s[12:13]
	s_nop 1
	v_mfma_f32_16x16x32_fp8_fp8 v[24:27], v[26:27], v[12:13], v[40:43]
	v_mfma_f32_16x16x32_fp8_fp8 v[20:23], v[22:23], v[12:13], v[36:39]
	s_nop 2
	v_mfma_f32_16x16x32_fp8_fp8 v[16:19], v[18:19], v[12:13], v[32:35]
	s_nop 2
	v_pk_add_f32 v[34:35], v[76:77], v[80:81]
	v_pk_add_f32 v[32:33], v[78:79], v[82:83]
	v_mfma_f32_16x16x32_fp8_fp8 v[12:15], v[14:15], v[12:13], v[28:31]
	s_nop 2
	v_cndmask_b32_e64 v31, 0, v57, s[0:1]
	v_cndmask_b32_e64 v30, 0, v56, s[0:1]
	v_pk_add_f32 v[28:29], v[72:73], v[34:35]
	s_nop 0
	v_mfma_f32_16x16x32_fp8_fp8 v[40:43], v[66:67], v[30:31], v[24:27]
	s_nop 2
	v_add_f32_e64 v24, v74, v32
	v_add_f32_e64 v25, v75, v33
	v_pk_add_f32 v[26:27], v[68:69], v[28:29]
	v_pk_add_f32 v[24:25], v[60:61], v[24:25]
	v_mfma_f32_16x16x32_fp8_fp8 v[36:39], v[62:63], v[30:31], v[20:23]
	v_mfma_f32_16x16x32_fp8_fp8 v[32:35], v[58:59], v[30:31], v[16:19]
	s_nop 1
	v_pk_mov_b32 v[20:21], v[26:27], v[24:25] op_sel:[1,0]
	v_mov_b32_e32 v27, v25
	v_pk_add_f32 v[20:21], v[20:21], v[26:27]
	v_mfma_f32_16x16x32_fp8_fp8 v[28:31], v[54:55], v[30:31], v[12:15]
	v_add_f32_e32 v16, v20, v21
	v_cndmask_b32_e64 v237, 0, v16, s[14:15]
	v_fmac_f32_e32 v237, v241, v84

.Lsel_done_2:
	v_mov_b32_e32 v236, s100
	s_nop 1
	v_mov_b32_e32 v234, s94
	v_mov_b32_e32 v235, s98
	v_lshlrev_b32_e32 v12, 12, v234
	s_waitcnt vmcnt(16)
	v_lshlrev_b32_e32 v52, 12, v235
	v_ashrrev_i32_e32 v13, 31, v12
	v_ashrrev_i32_e32 v53, 31, v52
	v_lshl_add_u64 v[14:15], v[200:201], 0, v[12:13]
	v_lshl_add_u64 v[12:13], v[198:199], 0, v[12:13]
	v_lshl_add_u64 v[54:55], v[200:201], 0, v[52:53]
	v_lshl_add_u64 v[52:53], v[198:199], 0, v[52:53]
	global_load_dwordx4 v[80:83], v[14:15], off
	global_load_dwordx4 v[76:79], v[14:15], off offset:1024
	global_load_dwordx4 v[72:75], v[14:15], off offset:2048
	global_load_dwordx4 v[68:71], v[14:15], off offset:3072
	global_load_dwordx4 v[24:27], v[12:13], off
	global_load_dwordx4 v[20:23], v[12:13], off offset:1024
	global_load_dwordx4 v[16:19], v[12:13], off offset:2048
	s_nop 0
	global_load_dwordx4 v[12:15], v[12:13], off offset:3072
	s_nop 0
	global_load_dwordx4 v[96:99], v[54:55], off
	global_load_dwordx4 v[92:95], v[54:55], off offset:1024
	global_load_dwordx4 v[88:91], v[54:55], off offset:2048
	global_load_dwordx4 v[84:87], v[54:55], off offset:3072
	global_load_dwordx4 v[64:67], v[52:53], off
	global_load_dwordx4 v[60:63], v[52:53], off offset:1024
	global_load_dwordx4 v[56:59], v[52:53], off offset:2048
	s_nop 0
	global_load_dwordx4 v[52:55], v[52:53], off offset:3072
	v_cmp_lt_u32_e64 s[0:1], s24, v231
	s_and_saveexec_b64 s[20:21], s[0:1]
	s_cbranch_execz .LBB0_577
	v_cmp_lt_i32_e64 s[0:1], -1, v240
	s_and_saveexec_b64 s[12:13], s[0:1]
	s_xor_b64 s[22:23], exec, s[12:13]
	s_cbranch_execz .LBB0_601
	v_lshlrev_b32_e32 v240, 1, v240
	v_cmp_ne_u32_e64 s[12:13], v208, v240
	v_cmp_ge_i32_e64 s[14:15], v1, v229
	v_cmp_eq_u32_e64 s[0:1], v208, v240
	s_or_b64 s[12:13], s[12:13], s[14:15]
	s_mov_b64 s[14:15], -1
	s_and_saveexec_b64 s[24:25], s[12:13]
	v_or_b32_e32 v1, 1, v240
	v_cmp_eq_u32_e64 s[12:13], v208, v1
	v_cmp_lt_i32_e64 s[14:15], v239, v229
	s_and_b64 s[12:13], s[12:13], s[14:15]
	s_orn2_b64 s[14:15], s[12:13], exec
	s_or_b64 exec, exec, s[24:25]
	v_cndmask_b32_e64 v245, 0, v151, s[0:1]
	v_cndmask_b32_e64 v244, 0, v150, s[0:1]
	v_cndmask_b32_e64 v247, 0, v11, s[0:1]
	v_cndmask_b32_e64 v246, 0, v10, s[0:1]
	s_waitcnt vmcnt(31)
	v_mfma_f32_16x16x32_fp8_fp8 v[240:243], v[128:129], v[244:245], 0
	s_and_b64 s[12:13], s[0:1], s[14:15]
	v_mfma_f32_16x16x32_fp8_fp8 v[128:131], v[130:131], v[246:247], v[240:243]
	s_nop 5
	v_cndmask_b32_e64 v241, v151, 0, s[0:1]
	v_cndmask_b32_e64 v240, v150, 0, s[0:1]
	v_cndmask_b32_e64 v243, v11, 0, s[0:1]
	v_cndmask_b32_e64 v242, v10, 0, s[0:1]
	s_waitcnt vmcnt(23)
	v_mfma_f32_16x16x32_fp8_fp8 v[128:131], v[144:145], v[240:241], v[128:131]
	s_xor_b64 s[0:1], s[0:1], -1
	s_and_b64 s[0:1], s[14:15], s[0:1]
	v_mfma_f32_16x16x32_fp8_fp8 v[128:131], v[146:147], v[242:243], v[128:131]
	v_mfma_f32_16x16x32_fp8_fp8 v[144:147], v[124:125], v[244:245], 0
	v_mfma_f32_16x16x32_fp8_fp8 v[124:127], v[126:127], v[246:247], v[144:147]
	s_nop 5
	s_waitcnt vmcnt(22)
	v_mfma_f32_16x16x32_fp8_fp8 v[124:127], v[140:141], v[240:241], v[124:127]
	v_max_f32_e32 v1, v128, v129
	v_mfma_f32_16x16x32_fp8_fp8 v[124:127], v[142:143], v[242:243], v[124:127]
	v_mfma_f32_16x16x32_fp8_fp8 v[140:143], v[120:121], v[244:245], 0
	v_mfma_f32_16x16x32_fp8_fp8 v[120:123], v[122:123], v[246:247], v[140:143]
	s_nop 5
	s_waitcnt vmcnt(21)
	v_mfma_f32_16x16x32_fp8_fp8 v[120:123], v[136:137], v[240:241], v[120:123]
	v_mfma_f32_16x16x32_fp8_fp8 v[120:123], v[138:139], v[242:243], v[120:123]
	v_mfma_f32_16x16x32_fp8_fp8 v[136:139], v[116:117], v[244:245], 0
	v_mfma_f32_16x16x32_fp8_fp8 v[116:119], v[118:119], v[246:247], v[136:139]
	s_nop 5
	s_waitcnt vmcnt(20)
	v_mfma_f32_16x16x32_fp8_fp8 v[116:119], v[132:133], v[240:241], v[116:119]
	v_max_f32_e32 v133, v126, v127
	v_max_f32_e32 v132, v130, v131
	v_max3_f32 v133, v124, v125, v133
	v_mfma_f32_16x16x32_fp8_fp8 v[116:119], v[134:135], v[242:243], v[116:119]
	v_max3_f32 v1, v1, v132, v133
	v_max_f32_e32 v132, v122, v123
	v_max3_f32 v132, v120, v121, v132
	s_nop 3
	s_nop 0
	v_max_f32_e32 v133, v118, v119
	v_max3_f32 v133, v116, v117, v133
	v_max3_f32 v1, v1, v132, v133
	ds_bpermute_b32 v132, v223, v1
	s_waitcnt lgkmcnt(0)
	v_max_f32_e32 v132, v132, v132
	v_max_f32_e32 v1, v1, v132
	ds_bpermute_b32 v132, v224, v1
	s_waitcnt lgkmcnt(0)
	v_max_f32_e32 v1, v1, v132
	v_mul_f32_e64 v1, v1, s76
	v_max_f32_e32 v1, v238, v1
	v_cndmask_b32_e64 v241, v238, v1, s[14:15]
	v_sub_f32_e32 v133, 0x41000000, v241
	v_fma_f32 v128, v128, s76, v133
	v_fma_f32 v129, v129, s76, v133
	v_fma_f32 v124, v124, s76, v133
	v_fma_f32 v125, v125, s76, v133
	v_exp_f32_e32 v128, v128
	v_exp_f32_e32 v129, v129
	v_exp_f32_e32 v124, v124
	v_exp_f32_e32 v125, v125
	v_sub_f32_e32 v1, v238, v241
	v_fma_f32 v130, v130, s76, v133
	v_fma_f32 v131, v131, s76, v133
	v_fma_f32 v126, v126, s76, v133
	v_fma_f32 v127, v127, s76, v133
	v_exp_f32_e32 v132, v1
	v_exp_f32_e32 v130, v130
	v_exp_f32_e32 v131, v131
	v_exp_f32_e32 v126, v126
	v_exp_f32_e32 v127, v127
	v_cvt_pk_fp8_f32 v136, v124, v125
	v_cvt_pk_fp8_f32 v1, v128, v129
	v_pk_mul_f32 v[42:43], v[42:43], v[132:133] op_sel_hi:[1,0]
	v_pk_mul_f32 v[40:41], v[40:41], v[132:133] op_sel_hi:[1,0]
	v_cvt_pk_fp8_f32 v136, v126, v127 op_sel:[0,0,1]
	v_cvt_pk_fp8_f32 v1, v130, v131 op_sel:[0,0,1]
	v_pk_mul_f32 v[34:35], v[34:35], v[132:133] op_sel_hi:[1,0]
	v_pk_mul_f32 v[32:33], v[32:33], v[132:133] op_sel_hi:[1,0]
	v_cndmask_b32_e64 v135, 0, v136, s[12:13]
	v_cndmask_b32_e64 v134, 0, v1, s[12:13]
	v_pk_mul_f32 v[30:31], v[30:31], v[132:133] op_sel_hi:[1,0]
	v_pk_mul_f32 v[28:29], v[28:29], v[132:133] op_sel_hi:[1,0]
	v_fma_f32 v120, v120, s76, v133
	v_fma_f32 v121, v121, s76, v133
	v_mfma_f32_16x16x32_fp8_fp8 v[40:43], v[48:49], v[134:135], v[40:43]
	v_fma_f32 v48, v116, s76, v133
	v_pk_mul_f32 v[38:39], v[38:39], v[132:133] op_sel_hi:[1,0]
	v_pk_mul_f32 v[36:37], v[36:37], v[132:133] op_sel_hi:[1,0]
	v_mfma_f32_16x16x32_fp8_fp8 v[32:35], v[6:7], v[134:135], v[32:35]
	v_exp_f32_e32 v120, v120
	v_exp_f32_e32 v121, v121
	v_fma_f32 v122, v122, s76, v133
	v_mfma_f32_16x16x32_fp8_fp8 v[28:31], v[2:3], v[134:135], v[28:31]
	v_cndmask_b32_e64 v2, 0, v1, s[0:1]
	v_fma_f32 v1, v117, s76, v133
	v_cndmask_b32_e64 v3, 0, v136, s[0:1]
	v_mfma_f32_16x16x32_fp8_fp8 v[36:39], v[44:45], v[134:135], v[36:39]
	v_exp_f32_e32 v44, v48
	v_exp_f32_e32 v45, v1
	v_fma_f32 v1, v118, s76, v133
	v_exp_f32_e32 v48, v1
	v_fma_f32 v1, v119, s76, v133
	v_fma_f32 v123, v123, s76, v133
	v_exp_f32_e32 v49, v1
	s_waitcnt vmcnt(17)
	v_mfma_f32_16x16x32_fp8_fp8 v[32:35], v[104:105], v[2:3], v[32:35]
	v_exp_f32_e32 v122, v122
	v_exp_f32_e32 v123, v123
	v_cvt_pk_fp8_f32 v104, v44, v45
	v_cvt_pk_fp8_f32 v1, v120, v121
	v_mfma_f32_16x16x32_fp8_fp8 v[36:39], v[108:109], v[2:3], v[36:39]
	v_cvt_pk_fp8_f32 v104, v48, v49 op_sel:[0,0,1]
	v_cvt_pk_fp8_f32 v1, v122, v123 op_sel:[0,0,1]
	v_mfma_f32_16x16x32_fp8_fp8 v[40:43], v[112:113], v[2:3], v[40:43]
	s_waitcnt vmcnt(16)
	v_mfma_f32_16x16x32_fp8_fp8 v[28:31], v[100:101], v[2:3], v[28:31]
	v_cndmask_b32_e64 v3, 0, v104, s[12:13]
	v_cndmask_b32_e64 v2, 0, v1, s[12:13]
	s_nop 1
	v_mfma_f32_16x16x32_fp8_fp8 v[36:39], v[46:47], v[2:3], v[36:39]
	v_mfma_f32_16x16x32_fp8_fp8 v[6:9], v[8:9], v[2:3], v[32:35]
	s_nop 2
	v_pk_add_f32 v[34:35], v[124:125], v[128:129]
	v_pk_add_f32 v[32:33], v[126:127], v[130:131]
	v_mfma_f32_16x16x32_fp8_fp8 v[40:43], v[50:51], v[2:3], v[40:43]
	v_add_f32_e64 v32, v122, v32
	v_add_f32_e64 v33, v123, v33
	v_mfma_f32_16x16x32_fp8_fp8 v[2:5], v[4:5], v[2:3], v[28:31]
	v_add_f32_e64 v32, v48, v32
	v_add_f32_e64 v33, v49, v33
	s_nop 0
	v_pk_add_f32 v[28:29], v[120:121], v[34:35]
	v_cndmask_b32_e64 v31, 0, v104, s[0:1]
	v_pk_add_f32 v[28:29], v[44:45], v[28:29]
	v_cndmask_b32_e64 v30, 0, v1, s[0:1]
	v_pk_mov_b32 v[34:35], v[28:29], v[32:33] op_sel:[1,0]
	v_mov_b32_e32 v29, v33
	v_pk_add_f32 v[28:29], v[34:35], v[28:29]
	v_mfma_f32_16x16x32_fp8_fp8 v[40:43], v[114:115], v[30:31], v[40:43]
	v_add_f32_e32 v1, v28, v29
	v_cndmask_b32_e64 v242, 0, v1, s[14:15]
	v_fmac_f32_e32 v242, v237, v132
	v_mfma_f32_16x16x32_fp8_fp8 v[36:39], v[110:111], v[30:31], v[36:39]
	v_mfma_f32_16x16x32_fp8_fp8 v[32:35], v[106:107], v[30:31], v[6:9]
	v_mfma_f32_16x16x32_fp8_fp8 v[28:31], v[102:103], v[30:31], v[2:5]
